# cand2 + XCD-local release at the three GEMM-to-GEMM seams, guarded at run time: taken only if the 8 blockIdx%8 groups sit on 8 distinct single XCCs and the grid is 256
# speedup vs baseline: 1.0032x; 1.0032x over previous
; #define LAS __attribute__((address_space(3)))
; __device__ __forceinline__ unsigned xb_add(unsigned* p, unsigned v) { return __hip_atomic_fetch_add(p, v, __ATOMIC_RELAXED, __HIP_MEMORY_SCOPE_AGENT); }
; __device__ __forceinline__ unsigned xb_xcc_id() { return (unsigned)__builtin_amdgcn_s_getreg((3 << 11) | 20) & 0xFu; }
; __device__ __forceinline__ XcdBarrier xcd_barrier_post(unsigned* bar, volatile LAS unsigned* st) {
;     XcdBarrier b; b.bar = bar; b.x = xb_xcc_id(); b.st = st;
;     if (threadIdx.x == 0) (void)xb_add(&bar[XB_XCNT(b.x)], 1u);
;     return b;
; __global__ void __launch_bounds__(NWAVES * 64, 2) skel_fwd(Args args) {
;     extern __shared__ __attribute__((aligned(16))) unsigned char lds[];
;     Frame F;
;     F.lds = (LAS unsigned char*)lds;
;     F.MISC = (volatile LAS unsigned*)(F.lds + MISC_OFF);
;     F.tid = threadIdx.x; F.lane = F.tid & 63; F.wave = __builtin_amdgcn_readfirstlane(F.tid >> 6);
;     F.G = gridDim.x; { const int bx = blockIdx.x; F.vcu = (F.G % 8 == 0) ? (bx % 8) * (F.G / 8) + bx / 8 : bx; }
;     unsigned char* ws = args.ws; F.ws = ws; F.out = args.out;
;     F.ctl = (gu32*)(ws + WS_CTL);
;     for (int u = F.tid; u < (LDS_BYTES - LDSCTL_OFF) / 4; u += NWAVES * 64) ((LAS unsigned*)(F.lds + LDSCTL_OFF))[u] = 0u;
;     __syncthreads();
;     XcdBarrier bar; bar.bar = (unsigned*)(F.ctl + CW_BAR); bar.x = 0; bar.st = nullptr;
;     if (!MK_PER_PHASE) bar = xcd_barrier_post((unsigned*)(F.ctl + CW_BAR), F.MISC + 8);
.LBB0_2:
	v_lshl_add_u32 v1, v0, 2, 0
	v_add_u32_e32 v1, 0x20000, v1
	v_mov_b32_e32 v2, 0
	ds_write2st64_b32 v1, v2, v2 offset1:8
	ds_write2st64_b32 v1, v2, v2 offset0:16 offset1:24
	v_or_b32_e32 v1, 0x800, v0
	s_mov_b64 s[2:3], -1
	s_and_saveexec_b64 s[4:5], s[2:3]
	v_lshl_add_u32 v3, v1, 2, 0
	v_add_u32_e32 v3, 0x20000, v3
	ds_write_b32 v3, v2
	s_or_b64 exec, exec, s[4:5]
	s_and_saveexec_b64 s[4:5], s[2:3]
	s_add_i32 s2, 0, 0x20000
	v_lshl_add_u32 v1, v1, 2, s2
	v_mov_b32_e32 v2, 0
	ds_write_b32 v1, v2 offset:2048
	s_or_b64 exec, exec, s[4:5]
	s_load_dwordx2 s[80:81], s[0:1], 0x80
	v_or_b32_e32 v1, 0xc00, v0
	v_cmp_gt_u32_e64 s[2:3], 7, 6
	v_cmp_gt_u32_e64 s[6:7], 7, 5
	s_and_saveexec_b64 s[4:5], s[6:7]
	v_lshl_add_u32 v2, v1, 2, 0
	v_add_u32_e32 v2, 0x20000, v2
	v_mov_b32_e32 v3, 0
	ds_write_b32 v2, v3
	s_or_b64 exec, exec, s[4:5]
	s_load_dwordx2 s[82:83], s[0:1], 0x88
	s_and_saveexec_b64 s[4:5], s[2:3]
	s_add_i32 s2, 0, 0x20000
	v_lshl_add_u32 v1, v1, 2, s2
	v_mov_b32_e32 v2, 0
	ds_write_b32 v1, v2 offset:2048
	s_or_b64 exec, exec, s[4:5]
	s_load_dwordx16 s[4:19], s[0:1], 0x0
	s_load_dwordx16 s[56:71], s[0:1], 0x40
	s_waitcnt lgkmcnt(0)
	s_barrier
	v_writelane_b32 v243, s4, 2
	s_add_u32 s84, s80, 0x4000
	s_getreg_b32 s0, hwreg(HW_REG_XCC_ID, 0, 4)
	v_writelane_b32 v243, s5, 3
	v_writelane_b32 v243, s6, 4
	v_writelane_b32 v243, s7, 5
	v_writelane_b32 v243, s8, 6
	v_writelane_b32 v243, s9, 7
	v_writelane_b32 v243, s10, 8
	v_writelane_b32 v243, s11, 9
	v_writelane_b32 v243, s12, 10
	v_writelane_b32 v243, s13, 11
	v_writelane_b32 v243, s14, 12
	v_writelane_b32 v243, s15, 13
	v_writelane_b32 v243, s16, 14
	v_writelane_b32 v243, s17, 15
	v_writelane_b32 v243, s18, 16
	s_addc_u32 s85, s81, 0
	s_and_b32 s26, s0, 15
	v_cmp_eq_u32_e64 s[86:87], 0, v0
	v_writelane_b32 v243, s19, 17
	s_and_saveexec_b64 s[0:1], s[86:87]
	s_cbranch_execz .LBB0_13
	s_mov_b64 s[2:3], exec
	v_mbcnt_lo_u32_b32 v1, s2, 0
	v_mbcnt_hi_u32_b32 v1, s3, v1
	v_cmp_eq_u32_e32 vcc, 0, v1
	s_and_b64 s[4:5], exec, vcc
	s_mov_b64 exec, s[4:5]
	s_cbranch_execz .LBB0_13
	s_lshl_b32 s4, s26, 8
	s_bcnt1_i32_b64 s2, s[2:3]
	v_mov_b32_e32 v1, s4
	v_mov_b32_e32 v2, s2
	global_atomic_add v1, v2, s[84:85] offset:1024
	s_and_b32 s4, s73, 7
	s_lshl_b32 s4, s4, 2
	s_add_u32 s4, s4, 0xc000
	s_lshl_b32 s5, 1, s26
	s_cmpk_eq_u32 s76, 0x100
	s_cbranch_scc1 .Lxm_g
	s_or_b32 s5, s5, 0x10000
.Lxm_g:
	v_mov_b32_e32 v1, s4
	v_mov_b32_e32 v2, s5
	global_atomic_or v1, v2, s[84:85]

; __device__ __forceinline__ unsigned xb_add(unsigned* p, unsigned v) { return __hip_atomic_fetch_add(p, v, __ATOMIC_RELAXED, __HIP_MEMORY_SCOPE_AGENT); }
; __device__ __forceinline__ void xcd_barrier(const XcdBarrier& b) {
;     ...
;         const unsigned old = xb_add(&bar[XB_XSUB(b.x)], 1u);
;         const unsigned gen = old / nloc;
;         if (old + 1u == (gen + 1u) * nloc) {
.LBB0_592:
	v_readlane_b32 s4, v243, 56
	s_lshl_b32 s4, s4, 2
	s_add_u32 s25, s2, s4
	s_addc_u32 s24, s3, 0
	v_mov_b32_e32 v1, s25
	v_add_co_u32_e32 v6, vcc, 0x1000, v1
	v_mov_b32_e32 v1, s24
	s_nop 0
	v_addc_co_u32_e32 v7, vcc, 0, v1, vcc
	v_mov_b32_e32 v245, 0xc000
	global_load_dwordx4 v[246:249], v245, s[2:3] sc1
	global_load_dwordx4 v[250:253], v245, s[2:3] offset:16 sc1
	flat_atomic_add v3, v[6:7], v217 offset:1024 sc0
	v_cvt_f32_u32_e32 v1, v4
	v_sub_u32_e32 v5, 0, v4
	v_rcp_iflag_f32_e32 v1, v1
	s_nop 0
	v_mul_f32_e32 v1, 0x4f7ffffe, v1
	v_cvt_u32_f32_e32 v1, v1
	v_mul_lo_u32 v5, v5, v1
	v_mul_hi_u32 v5, v1, v5
	v_add_u32_e32 v1, v1, v5
	s_waitcnt vmcnt(0) lgkmcnt(0)
	v_mul_hi_u32 v1, v3, v1
	v_mul_lo_u32 v5, v1, v4
	v_sub_u32_e32 v5, v3, v5
	v_cmp_ge_u32_e32 vcc, v5, v4
	v_add_u32_e32 v6, 1, v1
	v_add_u32_e32 v3, 1, v3
	v_cndmask_b32_e32 v1, v1, v6, vcc
	v_sub_u32_e32 v6, v5, v4
	v_cndmask_b32_e32 v5, v5, v6, vcc
	v_cmp_ge_u32_e32 vcc, v5, v4
	v_add_u32_e32 v5, 1, v1
	s_nop 0
	v_cndmask_b32_e32 v1, v1, v5, vcc
	v_mad_u64_u32 v[4:5], s[4:5], v4, v1, v[4:5]
	v_cmp_ne_u32_e32 vcc, v3, v4
	s_and_saveexec_b64 s[4:5], vcc
	s_xor_b64 s[4:5], exec, s[4:5]
	s_cbranch_execz .LBB0_605
	v_mov_b32_e32 v2, s25
	v_add_co_u32_e32 v2, vcc, 0x2000, v2
	v_mov_b32_e32 v3, s24
	s_nop 0
	v_addc_co_u32_e32 v3, vcc, 0, v3, vcc
	flat_load_dword v2, v[2:3] offset:1024 sc1
	s_add_u32 s8, s25, 0x2400
	s_addc_u32 s9, s24, 0
	s_waitcnt vmcnt(0) lgkmcnt(0)
	v_cmp_eq_u32_e32 vcc, v2, v1
	s_and_saveexec_b64 s[6:7], vcc
	s_cbranch_execz .LBB0_604
	s_mov_b32 s26, 1
	s_mov_b64 s[10:11], 0
	s_branch .LBB0_596

; __device__ __forceinline__ unsigned xb_ld(unsigned* p)              { return __hip_atomic_load(p, __ATOMIC_RELAXED, __HIP_MEMORY_SCOPE_AGENT); }
; __device__ __forceinline__ unsigned xb_add(unsigned* p, unsigned v) { return __hip_atomic_fetch_add(p, v, __ATOMIC_RELAXED, __HIP_MEMORY_SCOPE_AGENT); }
; #define XB_SPIN(cond, bar) do { unsigned _sp = 0; while (cond) { __builtin_amdgcn_s_sleep(1); \
;     if ((++_sp & 255u) == 0u) { if (xb_ld(&(bar)[XB_TMO])) break; if (_sp > XB_SPIN_CAP) { atomicAdd(&(bar)[XB_TMO], 1u); break; } } } } while (0)
; __device__ __forceinline__ void xcd_barrier(const XcdBarrier& b) {
;     ...
;         if (old + 1u == (gen + 1u) * nloc) {
;             __builtin_amdgcn_fence(__ATOMIC_RELEASE, "agent");
;             asm volatile("s_waitcnt vmcnt(0)" ::: "memory");
;             const unsigned og = xb_add(&bar[XB_TOP], 1u);
;             const unsigned tg = og / nx;
;             if (og + 1u == (tg + 1u) * nx) xb_add(&bar[XB_TOPGEN], 1u);
;             else XB_SPIN(xb_ld(&bar[XB_TOPGEN]) == tg, bar);
.LBB0_605:
	s_andn2_saveexec_b64 s[4:5], s[4:5]
	s_cbranch_execz .LBB0_621
	v_or3_b32 v254, v246, v247, v248
	v_or3_b32 v254, v254, v249, v250
	v_or3_b32 v254, v254, v251, v252
	v_or_b32_e32 v254, v254, v253
	v_bcnt_u32_b32 v255, v246, 0
	v_bcnt_u32_b32 v255, v247, v255
	v_bcnt_u32_b32 v255, v248, v255
	v_bcnt_u32_b32 v255, v249, v255
	v_bcnt_u32_b32 v255, v250, v255
	v_bcnt_u32_b32 v255, v251, v255
	v_bcnt_u32_b32 v255, v252, v255
	v_bcnt_u32_b32 v255, v253, v255
	v_bcnt_u32_b32 v254, v254, 0
	v_xor_b32_e32 v254, 8, v254
	v_xor_b32_e32 v255, 8, v255
	v_or_b32_e32 v254, v254, v255
	v_cmp_ne_u32_e32 vcc, 0, v254
	s_cbranch_vccnz .Lgl_0
	s_branch .Llb_0
